# mixa step loop: counted vmcnt waits (next-tile K/V prefetch no longer drained in the first QK block; retired before the ds_writes at step end)
# speedup vs baseline: 1.0034x; 1.0016x over previous
; __device__ __forceinline__ int v_rd_base(int lane) { return ((lane & 3) << 3) | (((lane >> 2) & 3) << 6) | (((lane >> 4) & 1) << 5) | (((lane >> 5) & 1) << 8); }
; #define MIXA_TWRITE(slot, K0, K1, V0, V1) do { *(bf16x8*)(K_lds + (slot) + kst0) = K0; *(bf16x8*)(K_lds + (slot) + kst1) = K1; \
;     *(bf16x8*)(V_lds + (slot) + vst0) = V0; *(bf16x8*)(V_lds + (slot) + vst1) = V1; } while (0)
; __device__ __forceinline__ void mixa_run(int b, int h, int br, int res, int n0, const bf16_t* __restrict__ proj, const float* __restrict__ btab,
;                                          bf16_t* __restrict__ OA, float* __restrict__ LSE, char* lds) {
;     ...
;   MIXA_TLOAD(n0 - 1, ak0, ak1, av0, av1); MIXA_TLOAD(n0, bk0, bk1, bv0, bv1);
;   if (tid < 192) { const int idx = tid - 32; bt[tid] = (idx >= 0 && idx <= 128) ? btab[(br * 8 + h) * 132 + idx] : -1.0e30f; ((float*)(lds + MIXA_LDS_NEG))[tid] = -1.0e30f; }
;   MIXA_TWRITE(0, ak0, ak1, av0, av1); MIXA_TWRITE(16384, bk0, bk1, bv0, bv1);
;   MIXA_TLOAD(n0 + 1, ak0, ak1, av0, av1); MIXA_TLOAD(n0 + 2, bk0, bk1, bv0, bv1);
;   bf16x8 qr[8];
;   { const size_t tokq = rowb + ((size_t)(64 * n0 + 32 * q32 + r32) << sh) + res; const bf16_t* Qp = proj + tokq * INW + h * 128 + hi * 8;
; #pragma unroll
;     for (int d0 = 0; d0 < 8; ++d0) qr[d0] = ld8(Qp + d0 * 16); }
;   MIXA_TWRITE(32768, ak0, ak1, av0, av1); MIXA_TWRITE(49152, bk0, bk1, bv0, bv1);
;   __syncthreads();
;   const float* btl = bt + (4 * hi - r32 + 32); const float* btn = (const float*)(lds + MIXA_LDS_NEG) + (4 * hi - r32 + 32);
;   const int vbl = (int)(uintptr_t)V_lds + v_rd_base(lane) + dh * 1024;
;   bf16_t* Ob0 = OA + (size_t)br * ((size_t)2 * SEQ * 1024) + h * 128 + dh * 64;
;   float* Lb = LSE + (size_t)br * ((size_t)2 * SEQ * 8) + h;
.LBB0_310:
	s_ashr_i32 s12, s3, 6
	s_lshl_b32 s11, s12, 7
	v_and_b32_e32 v7, 31, v36
	s_and_b32 s13, s12, 3
	s_add_i32 s11, s11, 0
	s_add_i32 s17, s11, 0x20400
	s_lshl_b32 s11, s13, 5
	v_or_b32_e32 v2, s85, v7
	s_lshl_b64 s[46:47], s[8:9], 13
	v_or_b32_e32 v2, s11, v2
	v_mov_b32_e32 v3, v114
	v_lshlrev_b64 v[2:3], s29, v[2:3]
	s_or_b32 s46, s46, s70
	v_lshl_add_u64 v[2:3], v[2:3], 0, s[46:47]
	v_mov_b64_e32 v[4:5], s[44:45]
	v_mad_u64_u32 v[4:5], s[8:9], v2, s1, v[4:5]
	v_mov_b32_e32 v2, v5
	v_mad_u64_u32 v[2:3], s[8:9], v3, s1, v[2:3]
	v_bfe_u32 v8, v36, 5, 1
	v_mov_b32_e32 v5, v2
	s_lshl_b32 s48, s7, 1
	v_lshl_add_u64 v[2:3], v[4:5], 0, s[48:49]
	v_lshlrev_b32_e32 v4, 4, v8
	v_mov_b32_e32 v5, v114
	v_lshl_add_u64 v[2:3], v[2:3], 0, v[4:5]
	global_load_dwordx4 v[118:121], v[2:3], off
	global_load_dwordx4 v[122:125], v[2:3], off offset:32
	global_load_dwordx4 v[126:129], v[2:3], off offset:64
	global_load_dwordx4 v[130:133], v[2:3], off offset:96
	global_load_dwordx4 v[134:137], v[2:3], off offset:128
	global_load_dwordx4 v[138:141], v[2:3], off offset:160
	global_load_dwordx4 v[142:145], v[2:3], off offset:192
	global_load_dwordx4 v[146:149], v[2:3], off offset:224
	s_add_i32 s7, 0, 0x18000
	v_add_u32_e32 v2, s7, v196
	s_waitcnt vmcnt(15)
	ds_write_b128 v34, v[82:85] offset:32768
	s_waitcnt vmcnt(14)
	ds_write_b128 v30, v[86:89] offset:32768
	s_waitcnt vmcnt(13)
	ds_write_b128 v2, v[90:93]
	v_add_u32_e32 v2, s7, v197
	s_add_i32 s7, 0, 0x1c000
	s_ashr_i32 s16, s3, 8
	s_waitcnt vmcnt(12)
	ds_write_b128 v2, v[94:97]
	s_waitcnt vmcnt(11)
	ds_write_b128 v34, v[98:101] offset:49152
	s_waitcnt vmcnt(10)
	ds_write_b128 v30, v[102:105] offset:49152
	v_add_u32_e32 v2, s7, v196
	v_and_b32_e32 v6, 63, v36
	s_waitcnt vmcnt(9)
	ds_write_b128 v2, v[106:109]
	v_add_u32_e32 v2, s7, v197
	s_lshl_b32 s7, s16, 10
	v_lshlrev_b32_e32 v3, 3, v6
	v_lshlrev_b32_e32 v9, 4, v36
	v_lshlrev_b32_e32 v11, 1, v36
	s_cmp_lg_u32 s10, -1
	s_waitcnt vmcnt(8)
	ds_write_b128 v2, v[110:113]
	v_lshlrev_b32_e32 v2, 2, v8
	v_and_b32_e32 v8, 24, v3
	v_and_b32_e32 v10, 0xc0, v9
	v_and_b32_e32 v11, 32, v11
	s_cselect_b32 s8, s10, 0
	v_or3_b32 v8, v8, v10, v11
	v_and_b32_e32 v3, 0x100, v3
	s_add_i32 s7, s7, s8
	v_add3_u32 v3, s7, v3, v8
	s_ashr_i32 s7, s6, 31
	s_lshl_b64 s[8:9], s[6:7], 25
	v_readlane_b32 s10, v254, 7
	s_add_u32 s8, s10, s8
	v_readlane_b32 s10, v254, 8
	s_addc_u32 s9, s10, s9
	s_add_u32 s10, s8, s48
	s_addc_u32 s22, s9, 0
	s_lshl_b32 s8, s16, 6
	s_ashr_i32 s9, s8, 31
	s_lshl_b64 s[8:9], s[8:9], 1
	s_add_u32 s8, s10, s8
	s_addc_u32 s9, s22, s9
	s_lshl_b64 s[6:7], s[6:7], 19
	v_readlane_b32 s10, v254, 11
	s_add_u32 s6, s10, s6
	s_addc_u32 s7, s20, s7
	s_lshl_b32 s2, s2, 2
	s_add_u32 s50, s6, s2
	s_addc_u32 s51, s7, 0
	s_add_u32 s6, s44, s48
	s_addc_u32 s7, s45, 0
	v_lshl_add_u64 v[154:155], s[6:7], 0, v[4:5]
	s_lshl_b32 s10, s13, 13
	s_add_i32 s7, s13, 3
	s_bfe_u32 s87, s12, 0x10001
	s_lshl_b32 s2, s12, 13
	s_add_i32 s12, s10, 0x2000
	s_lshl_b32 s16, s7, 13
	s_and_b32 s2, s2, 0x2000
	s_and_b32 s6, s12, 0x2000
	s_and_b32 s22, s16, 0x2000
	s_cmpk_lt_u32 s3, 0x100
	v_add_u32_e32 v201, s2, v3
	v_cmp_gt_u32_e64 s[40:41], 32, v6
	s_cselect_b64 s[2:3], -1, 0
	s_and_b64 s[52:53], s[2:3], s[40:41]
	s_movk_i32 s2, 0x70
	v_bitop3_b32 v216, v4, v9, s2 bitop3:0x78
	s_and_b32 s2, s10, 0x2000
	v_lshlrev_b32_e32 v8, 8, v7
	s_add_i32 s2, s2, 0
	v_and_b32_e32 v10, 0x70, v9
	v_add_u32_e32 v217, s2, v8
	s_movk_i32 s2, 0x60
	v_bitop3_b32 v220, v4, v10, s2 bitop3:0x36
	s_movk_i32 s2, 0x80
	v_bitop3_b32 v221, v4, v10, s2 bitop3:0x36
	s_movk_i32 s2, 0xa0
	v_bitop3_b32 v222, v4, v10, s2 bitop3:0x36
	s_movk_i32 s2, 0xc0
	v_bitop3_b32 v223, v4, v10, s2 bitop3:0x36
	s_movk_i32 s2, 0xe0
	v_bitop3_b32 v224, v4, v10, s2 bitop3:0x36
	s_add_i32 s2, s6, 0
	s_add_i32 s3, s10, 0x4000
	v_add_u32_e32 v225, s2, v8
	s_and_b32 s2, s3, 0x2000
	s_add_i32 s2, s2, 0
	v_add_u32_e32 v226, s2, v8
	s_add_i32 s2, s22, 0
	v_add_u32_e32 v227, s2, v8
	s_or_b32 s2, s13, 4
	s_cmp_lt_u32 s13, 2
	s_cselect_b64 s[54:55], -1, 0
	s_cmp_eq_u32 s13, 0
	v_add_u32_e32 v213, s6, v3
	s_cselect_b64 s[56:57], -1, 0
	s_add_i32 s38, 0, 0x20000
	s_and_b32 s6, s7, 6
	s_cmp_lg_u32 s6, 6
	s_cselect_b64 s[58:59], -1, 0
	s_and_b32 s2, s2, 6
	s_cmp_lg_u32 s2, 6
	s_cselect_b64 s[60:61], -1, 0
	s_lshl_b32 s48, 1, s29
	s_lshl_b64 s[62:63], s[48:49], 11
	s_lshl_b32 s48, 2, s29
	s_lshl_b64 s[74:75], s[48:49], 11
	s_lshl_b32 s48, 3, s29
	s_lshl_b64 s[82:83], s[48:49], 11
	s_lshl_b32 s48, 8, s29
	s_lshl_b64 s[34:35], s[48:49], 11
	s_lshl_b32 s48, 9, s29
	s_lshl_b64 s[90:91], s[48:49], 11
	s_lshl_b32 s48, 10, s29
	s_lshl_b64 s[66:67], s[48:49], 11
	s_lshl_b32 s48, 11, s29
	s_lshl_b64 s[88:89], s[48:49], 11
	s_lshl_b32 s48, 16, s29
	s_lshl_b64 s[36:37], s[48:49], 11
	s_lshl_b32 s48, 17, s29
	s_lshl_b64 s[92:93], s[48:49], 11
	s_lshl_b32 s48, 18, s29
	s_lshl_b64 s[94:95], s[48:49], 11
	s_lshl_b32 s48, 19, s29
	s_lshl_b64 s[96:97], s[48:49], 11
	s_lshl_b32 s48, 24, s29
	s_lshl_b64 s[78:79], s[48:49], 11
	s_lshl_b32 s48, 25, s29
	v_sub_u32_e32 v200, v2, v7
	v_add_u32_e32 v214, s22, v3
	v_lshlrev_b32_e32 v2, s29, v2
	v_lshlrev_b32_e32 v3, 1, v7
	s_lshl_b64 s[76:77], s[48:49], 11
	s_lshl_b32 s48, 26, s29
	v_lshl_or_b32 v2, v2, 11, v3
	v_mov_b32_e32 v3, v114
	s_lshl_b64 s[6:7], s[48:49], 11
	s_lshl_b32 s48, 27, s29
	s_bitset1_b32 s10, 15
	s_add_i32 s24, s85, s11
	s_mov_b32 s86, 0
	v_lshl_add_u32 v215, v7, 2, s17
	v_lshl_add_u64 v[156:157], s[8:9], 0, v[2:3]
	v_bitop3_b32 v218, v4, v10, 32 bitop3:0x36
	v_bitop3_b32 v219, v4, v10, 64 bitop3:0x36
	v_lshl_add_u32 v228, v200, 2, s38
	v_add_u32_e32 v229, s17, v4
	s_lshl_b64 s[8:9], s[48:49], 11
	s_lshl_b32 s39, s87, 14
	s_and_b32 s48, s10, 0xc000
	s_and_b32 s2, s16, 0xc000
	s_and_b32 s3, s3, 0xc000
	s_and_b32 s23, s12, 0xc000
	s_lshl_b32 s72, s84, 14
	v_add_u32_e32 v158, s24, v7
	v_mov_b32_e32 v159, v114
	s_mov_b64 s[10:11], 0
	s_mov_b32 s22, 0
	s_waitcnt vmcnt(0) lgkmcnt(0)
	s_barrier
	s_branch .LBB0_312

; __device__ __forceinline__ void mixa_run(int b, int h, int br, int res, int n0, const bf16_t* __restrict__ proj, const float* __restrict__ btab,
;                                          bf16_t* __restrict__ OA, float* __restrict__ LSE, char* lds) {
;     ...
;   for (int s = 0; s < MIXA_RUN / 2; ++s) {
;     const int nq = n0 + 2 * s, T0 = nq - 1; const bool more = (s + 1 < MIXA_RUN / 2);
;     if (more) { MIXA_TLOAD(T0 + 4, ak0, ak1, av0, av1); MIXA_TLOAD(T0 + 5, bk0, bk1, bv0, bv1); }
;     f32x16 p[5];
; #pragma unroll
;     for (int kb = 0; kb < 5; ++kb) { p[kb] = f32x16{}; const int brow = q32 + kb; const int sl = ((2 * s + (brow >> 1)) & 3) * 16384 + (brow & 1) * 8192;
.LBB0_317:
	s_waitcnt vmcnt(40)
; #define SBAR() __builtin_amdgcn_sched_barrier(0)
; __device__ __forceinline__ void mixa_run(int b, int h, int br, int res, int n0, const bf16_t* __restrict__ proj, const float* __restrict__ btab,
;                                          bf16_t* __restrict__ OA, float* __restrict__ LSE, char* lds) {
;     ...
;     f32x16 p[5];
; #pragma unroll
;     for (int kb = 0; kb < 5; ++kb) { p[kb] = f32x16{}; const int brow = q32 + kb; const int sl = ((2 * s + (brow >> 1)) & 3) * 16384 + (brow & 1) * 8192;
; #pragma unroll
;       for (int d0 = 0; d0 < 8; ++d0) { const int cb = (d0 * 16 + hi * 8) * 2;
;         const bf16x8 a = *reinterpret_cast<const bf16x8*>(K_lds + sl + KSWZ(r32, cb));
;         p[kb] = __builtin_amdgcn_mfma_f32_32x32x16_bf16(a, qr[d0], p[kb], 0, 0, 0); }
;       SBAR(); }
;     const size_t tokq = rowb + ((size_t)(64 * nq + 32 * q32 + r32) << sh) + res;
;     if (more) { const bf16_t* Qp = proj + (tokq + ((size_t)128 << sh)) * INW + h * 128 + hi * 8;
; #pragma unroll
;       for (int d0 = 0; d0 < 8; ++d0) qr[d0] = ld8(Qp + d0 * 16); }
.Lmixa_qk:
	s_add_i32 s68, s39, s22
	s_and_b32 s16, s68, 0xc000
	v_add_u32_e32 v6, s16, v217
	v_add_u32_e32 v2, v6, v216
	ds_read_b128 v[2:5], v2
	s_waitcnt lgkmcnt(0)
	v_mfma_f32_32x32x16_bf16 v[66:81], v[2:5], v[118:121], 0
	v_add_u32_e32 v2, v6, v218
	ds_read_b128 v[2:5], v2
	s_waitcnt lgkmcnt(0)
	v_mfma_f32_32x32x16_bf16 v[66:81], v[2:5], v[122:125], v[66:81]
	v_add_u32_e32 v2, v6, v219
	ds_read_b128 v[2:5], v2
	s_waitcnt lgkmcnt(0)
	v_mfma_f32_32x32x16_bf16 v[66:81], v[2:5], v[126:129], v[66:81]
	v_add_u32_e32 v2, v6, v220
	ds_read_b128 v[2:5], v2
	s_waitcnt lgkmcnt(0)
	v_mfma_f32_32x32x16_bf16 v[66:81], v[2:5], v[130:133], v[66:81]
	v_add_u32_e32 v2, v6, v221
	ds_read_b128 v[2:5], v2
	s_waitcnt lgkmcnt(0)
	v_mfma_f32_32x32x16_bf16 v[66:81], v[2:5], v[134:137], v[66:81]
	v_add_u32_e32 v2, v6, v222
	ds_read_b128 v[2:5], v2
	s_waitcnt lgkmcnt(0)
	v_mfma_f32_32x32x16_bf16 v[66:81], v[2:5], v[138:141], v[66:81]
	v_add_u32_e32 v2, v6, v223
	ds_read_b128 v[2:5], v2
	s_waitcnt lgkmcnt(0)
	v_mfma_f32_32x32x16_bf16 v[66:81], v[2:5], v[142:145], v[66:81]
	v_add_u32_e32 v2, v6, v224
	ds_read_b128 v[2:5], v2
	s_waitcnt lgkmcnt(0)
	v_mfma_f32_32x32x16_bf16 v[66:81], v[2:5], v[146:149], v[66:81]
	s_add_i32 s16, s23, s22
	s_and_b32 s69, s16, 0xc000
	v_add_u32_e32 v6, s69, v225
	v_add_u32_e32 v2, v6, v216
	ds_read_b128 v[2:5], v2
	s_waitcnt lgkmcnt(0)
	v_mfma_f32_32x32x16_bf16 v[50:65], v[2:5], v[118:121], 0
	v_add_u32_e32 v2, v6, v218
	ds_read_b128 v[2:5], v2
	s_waitcnt lgkmcnt(0)
	v_mfma_f32_32x32x16_bf16 v[50:65], v[2:5], v[122:125], v[50:65]
	v_add_u32_e32 v2, v6, v219
	ds_read_b128 v[2:5], v2
	s_waitcnt lgkmcnt(0)
	v_mfma_f32_32x32x16_bf16 v[50:65], v[2:5], v[126:129], v[50:65]
	v_add_u32_e32 v2, v6, v220
	ds_read_b128 v[2:5], v2
	s_waitcnt lgkmcnt(0)
	v_mfma_f32_32x32x16_bf16 v[50:65], v[2:5], v[130:133], v[50:65]
	v_add_u32_e32 v2, v6, v221
	ds_read_b128 v[2:5], v2
	s_waitcnt lgkmcnt(0)
	v_mfma_f32_32x32x16_bf16 v[50:65], v[2:5], v[134:137], v[50:65]
	v_add_u32_e32 v2, v6, v222
	ds_read_b128 v[2:5], v2
	s_waitcnt lgkmcnt(0)
	v_mfma_f32_32x32x16_bf16 v[50:65], v[2:5], v[138:141], v[50:65]
	v_add_u32_e32 v2, v6, v223
	ds_read_b128 v[2:5], v2
	s_waitcnt lgkmcnt(0)
	v_mfma_f32_32x32x16_bf16 v[50:65], v[2:5], v[142:145], v[50:65]
	v_add_u32_e32 v2, v6, v224
	ds_read_b128 v[2:5], v2
	s_waitcnt lgkmcnt(0)
	v_mfma_f32_32x32x16_bf16 v[50:65], v[2:5], v[146:149], v[50:65]
	s_add_i32 s16, s3, s22
	s_and_b32 s25, s16, 0xc000
	v_add_u32_e32 v6, s25, v226
	v_add_u32_e32 v2, v6, v216
	ds_read_b128 v[2:5], v2
	s_waitcnt lgkmcnt(0)
	v_mfma_f32_32x32x16_bf16 v[34:49], v[2:5], v[118:121], 0
	v_add_u32_e32 v2, v6, v218
	ds_read_b128 v[2:5], v2
	s_waitcnt lgkmcnt(0)
	v_mfma_f32_32x32x16_bf16 v[34:49], v[2:5], v[122:125], v[34:49]
	v_add_u32_e32 v2, v6, v219
	ds_read_b128 v[2:5], v2
	s_waitcnt lgkmcnt(0)
	v_mfma_f32_32x32x16_bf16 v[34:49], v[2:5], v[126:129], v[34:49]
	v_add_u32_e32 v2, v6, v220
	ds_read_b128 v[2:5], v2
	s_waitcnt lgkmcnt(0)
	v_mfma_f32_32x32x16_bf16 v[34:49], v[2:5], v[130:133], v[34:49]
	v_add_u32_e32 v2, v6, v221
	ds_read_b128 v[2:5], v2
	s_waitcnt lgkmcnt(0)
	v_mfma_f32_32x32x16_bf16 v[34:49], v[2:5], v[134:137], v[34:49]
	v_add_u32_e32 v2, v6, v222
	ds_read_b128 v[2:5], v2
	s_waitcnt lgkmcnt(0)
	v_mfma_f32_32x32x16_bf16 v[34:49], v[2:5], v[138:141], v[34:49]
	v_add_u32_e32 v2, v6, v223
	ds_read_b128 v[2:5], v2
	s_waitcnt lgkmcnt(0)
	v_mfma_f32_32x32x16_bf16 v[34:49], v[2:5], v[142:145], v[34:49]
	v_add_u32_e32 v2, v6, v224
	ds_read_b128 v[2:5], v2
	s_waitcnt lgkmcnt(0)
	v_mfma_f32_32x32x16_bf16 v[34:49], v[2:5], v[146:149], v[34:49]
	s_add_i32 s16, s2, s22
	s_and_b32 s26, s16, 0xc000
	v_add_u32_e32 v6, s26, v227
	v_add_u32_e32 v2, v6, v216
	ds_read_b128 v[2:5], v2
	s_waitcnt lgkmcnt(0)
	v_mfma_f32_32x32x16_bf16 v[18:33], v[2:5], v[118:121], 0
	v_add_u32_e32 v2, v6, v218
	ds_read_b128 v[2:5], v2
	s_waitcnt lgkmcnt(0)
	v_mfma_f32_32x32x16_bf16 v[18:33], v[2:5], v[122:125], v[18:33]
	v_add_u32_e32 v2, v6, v219
	ds_read_b128 v[2:5], v2
	s_waitcnt lgkmcnt(0)
	v_mfma_f32_32x32x16_bf16 v[18:33], v[2:5], v[126:129], v[18:33]
	v_add_u32_e32 v2, v6, v220
	ds_read_b128 v[2:5], v2
	s_waitcnt lgkmcnt(0)
	v_mfma_f32_32x32x16_bf16 v[18:33], v[2:5], v[130:133], v[18:33]
	v_add_u32_e32 v2, v6, v221
	ds_read_b128 v[2:5], v2
	s_waitcnt lgkmcnt(0)
	v_mfma_f32_32x32x16_bf16 v[18:33], v[2:5], v[134:137], v[18:33]
	v_add_u32_e32 v2, v6, v222
	ds_read_b128 v[2:5], v2
	s_waitcnt lgkmcnt(0)
	v_mfma_f32_32x32x16_bf16 v[18:33], v[2:5], v[138:141], v[18:33]
	v_add_u32_e32 v2, v6, v223
	ds_read_b128 v[2:5], v2
	s_waitcnt lgkmcnt(0)
	v_mfma_f32_32x32x16_bf16 v[18:33], v[2:5], v[142:145], v[18:33]
	v_add_u32_e32 v2, v6, v224
	ds_read_b128 v[2:5], v2
	s_waitcnt lgkmcnt(0)
	v_mfma_f32_32x32x16_bf16 v[18:33], v[2:5], v[146:149], v[18:33]
	s_add_i32 s16, s48, s22
	s_and_b32 s16, s16, 0xc000
	v_add_u32_e32 v115, s16, v217
	v_add_u32_e32 v2, v115, v216
	ds_read_b128 v[2:5], v2
	v_add_u32_e32 v116, v115, v218
	ds_read_b128 v[160:163], v116
	v_add_u32_e32 v116, v115, v219
	s_waitcnt lgkmcnt(1)
	v_mfma_f32_32x32x16_bf16 v[2:17], v[2:5], v[118:121], 0
	s_waitcnt lgkmcnt(0)
	v_mfma_f32_32x32x16_bf16 v[2:17], v[160:163], v[122:125], v[2:17]
	ds_read_b128 v[160:163], v116
	v_add_u32_e32 v116, v115, v220
	s_waitcnt lgkmcnt(0)
	v_mfma_f32_32x32x16_bf16 v[2:17], v[160:163], v[126:129], v[2:17]
	ds_read_b128 v[160:163], v116
	v_add_u32_e32 v116, v115, v221
	s_waitcnt lgkmcnt(0)
	v_mfma_f32_32x32x16_bf16 v[2:17], v[160:163], v[130:133], v[2:17]
	ds_read_b128 v[160:163], v116
	v_add_u32_e32 v116, v115, v222
	s_waitcnt lgkmcnt(0)
	v_mfma_f32_32x32x16_bf16 v[2:17], v[160:163], v[134:137], v[2:17]
	ds_read_b128 v[160:163], v116
	v_add_u32_e32 v116, v115, v223
	v_add_u32_e32 v115, v115, v224
	s_waitcnt lgkmcnt(0)
	v_mfma_f32_32x32x16_bf16 v[2:17], v[160:163], v[138:141], v[2:17]
	ds_read_b128 v[160:163], v116
	s_waitcnt lgkmcnt(0)
	v_mfma_f32_32x32x16_bf16 v[2:17], v[160:163], v[142:145], v[2:17]
	ds_read_b128 v[160:163], v115
	s_waitcnt lgkmcnt(0)
	v_mfma_f32_32x32x16_bf16 v[2:17], v[160:163], v[146:149], v[2:17]
	v_cndmask_b32_e64 v115, 0, 1, s[12:13]
	v_cmp_ne_u32_e64 s[42:43], 1, v115
	s_andn2_b64 vcc, exec, s[12:13]
	v_lshl_add_u64 v[116:117], v[158:159], 0, s[10:11]
	s_cbranch_vccnz .LBB0_319
	v_lshl_add_u64 v[118:119], v[116:117], 0, s[64:65]
	v_lshlrev_b64 v[118:119], s29, v[118:119]
	v_lshl_add_u64 v[118:119], v[118:119], 0, s[46:47]
	v_mad_u64_u32 v[146:147], s[12:13], v118, s1, v[154:155]
	v_mov_b32_e32 v118, v147
	v_mad_u64_u32 v[118:119], s[12:13], v119, s1, v[118:119]
	v_mov_b32_e32 v147, v118
	global_load_dwordx4 v[118:121], v[146:147], off
	global_load_dwordx4 v[122:125], v[146:147], off offset:32
	global_load_dwordx4 v[126:129], v[146:147], off offset:64
	global_load_dwordx4 v[130:133], v[146:147], off offset:96
	global_load_dwordx4 v[134:137], v[146:147], off offset:128
	global_load_dwordx4 v[138:141], v[146:147], off offset:160
	global_load_dwordx4 v[142:145], v[146:147], off offset:192
	s_nop 0
	global_load_dwordx4 v[146:149], v[146:147], off offset:224

; #define MIXA_TWRITE(slot, K0, K1, V0, V1) do { *(bf16x8*)(K_lds + (slot) + kst0) = K0; *(bf16x8*)(K_lds + (slot) + kst1) = K1; \
;     *(bf16x8*)(V_lds + (slot) + vst0) = V0; *(bf16x8*)(V_lds + (slot) + vst1) = V1; } while (0)
; __device__ __forceinline__ void mixa_run(int b, int h, int br, int res, int n0, const bf16_t* __restrict__ proj, const float* __restrict__ btab,
;                                          bf16_t* __restrict__ OA, float* __restrict__ LSE, char* lds) {
;     ...
;     __syncthreads();
;     if (more) { MIXA_TWRITE(((2 * s) & 3) * 16384, ak0, ak1, av0, av1); MIXA_TWRITE(((2 * s + 1) & 3) * 16384, bk0, bk1, bv0, bv1); }
;     __syncthreads();
.LBB0_323:
	s_or_b64 exec, exec, s[12:13]
	s_and_b64 vcc, exec, s[42:43]
	s_barrier
	s_cbranch_vccnz .LBB0_311
	s_waitcnt vmcnt(40)
	s_and_b32 s12, s22, 0x8000
	s_add_i32 s13, s12, 0
	v_add_u32_e32 v2, s13, v180
	v_add_u32_e32 v3, s13, v195
	s_add_i32 s13, s13, 0x10000
	v_add_u32_e32 v4, s13, v196
	ds_write_b128 v2, v[82:85]
	ds_write_b128 v3, v[86:89]
	ds_write_b128 v4, v[90:93]
	v_add_u32_e32 v4, s13, v197
	s_bitset1_b32 s12, 14
	ds_write_b128 v4, v[94:97]
	ds_write_b128 v2, v[98:101] offset:16384
	ds_write_b128 v3, v[102:105] offset:16384
	v_add_u32_e32 v2, s12, v198
	ds_write_b128 v2, v[106:109]
	v_add_u32_e32 v2, s12, v199
	ds_write_b128 v2, v[110:113]
	s_branch .LBB0_311
.Lmixa_laststep:
	s_waitcnt vmcnt(32)
	s_branch .Lmixa_qk
